# GEMM2 epilogue: the single vmcnt(0) after the 12 residual/gate loads split into staged counted waits (8,10,12,14,14) so the first row groups start when their own loads land
# baseline (speedup 1.0000x reference)
.LBB0_795:
	s_sub_i32 s10, s0, 64
	s_lshr_b32 s10, s10, 6
	s_lshr_b32 s1, s0, 3
	s_add_i32 s10, s10, 8
	s_cmp_lt_i32 s0, 64
	s_cselect_b32 s0, s1, s10
	v_or_b32_e32 v228, 16, v210
	v_or_b32_e32 v222, s46, v241
	s_mulk_i32 s0, 0xc00
	v_ashrrev_i32_e32 v229, 31, v228
	s_ashr_i32 s1, s0, 31
	v_ashrrev_i32_e32 v223, 31, v222
	v_lshlrev_b64 v[154:155], 11, v[228:229]
	v_or_b32_e32 v224, 32, v210
	s_lshl_b64 s[0:1], s[0:1], 2
	v_lshl_add_u64 v[154:155], s[60:61], 0, v[154:155]
	v_lshlrev_b64 v[246:247], 1, v[222:223]
	v_ashrrev_i32_e32 v225, 31, v224
	s_add_u32 s0, s80, s0
	v_lshl_add_u64 v[230:231], v[154:155], 0, v[246:247]
	v_lshlrev_b64 v[154:155], 11, v[224:225]
	v_or_b32_e32 v218, 48, v210
	s_addc_u32 s1, s81, s1
	v_lshl_add_u64 v[154:155], s[60:61], 0, v[154:155]
	v_ashrrev_i32_e32 v219, 31, v218
	v_lshl_add_u64 v[118:119], v[222:223], 2, s[0:1]
	v_lshl_add_u64 v[226:227], v[154:155], 0, v[246:247]
	v_lshlrev_b64 v[154:155], 11, v[218:219]
	global_load_dwordx4 v[122:125], v[118:119], off offset:16
	global_load_dwordx4 v[126:129], v[118:119], off
	global_load_dwordx4 v[110:113], v[118:119], off offset:528
	s_nop 0
	global_load_dwordx4 v[118:121], v[118:119], off offset:512
	v_lshl_add_u64 v[154:155], s[60:61], 0, v[154:155]
	v_lshl_add_u64 v[220:221], v[154:155], 0, v[246:247]
	global_load_dwordx4 v[182:185], v[230:231], off
	global_load_dwordx4 v[178:181], v[230:231], off offset:256
	global_load_dwordx4 v[174:177], v[226:227], off
	global_load_dwordx4 v[170:173], v[226:227], off offset:256
	global_load_dwordx4 v[166:169], v[220:221], off
	global_load_dwordx4 v[162:165], v[220:221], off offset:256
	v_and_b32_e32 v155, 64, v237
	v_xor_b32_e32 v154, 16, v237
	v_add_u32_e32 v155, 64, v155
	v_cmp_lt_i32_e32 vcc, v154, v155
	v_add_u32_e32 v214, 0x80, v210
	s_nop 0
	v_cndmask_b32_e32 v154, v237, v154, vcc
	v_lshlrev_b32_e32 v244, 2, v154
	v_xor_b32_e32 v154, 32, v237
	v_cmp_lt_i32_e32 vcc, v154, v155
	s_nop 1
	v_cndmask_b32_e32 v154, v237, v154, vcc
	v_lshlrev_b32_e32 v243, 2, v154
	v_ashrrev_i32_e32 v215, 31, v214
	v_lshlrev_b64 v[154:155], 11, v[214:215]
	v_lshl_add_u64 v[154:155], s[60:61], 0, v[154:155]
	v_lshl_add_u64 v[216:217], v[154:155], 0, v[246:247]
	global_load_dwordx4 v[158:161], v[216:217], off
	global_load_dwordx4 v[154:157], v[216:217], off offset:256
	v_lshl_add_u64 v[212:213], v[212:213], 0, v[246:247]
	s_waitcnt vmcnt(8)
	v_cvt_f32_f16_sdwa v247, v6 dst_sel:DWORD dst_unused:UNUSED_PAD src0_sel:WORD_1
	v_cvt_f32_f16_e32 v246, v6
	v_cvt_f32_f16_sdwa v251, v7 dst_sel:DWORD dst_unused:UNUSED_PAD src0_sel:WORD_1
	v_cvt_f32_f16_e32 v250, v7
	v_cvt_f32_f16_sdwa v249, v8 dst_sel:DWORD dst_unused:UNUSED_PAD src0_sel:WORD_1
	v_cvt_f32_f16_sdwa v253, v9 dst_sel:DWORD dst_unused:UNUSED_PAD src0_sel:WORD_1
	v_cvt_f32_f16_e32 v252, v9
	v_cvt_f32_f16_e32 v248, v8
	v_pk_fma_f32 v[152:153], v[152:153], v[128:129], v[250:251]
	v_pk_fma_f32 v[150:151], v[150:151], v[126:127], v[246:247]
	v_pk_fma_f32 v[246:247], v[148:149], v[124:125], v[252:253]
	v_pk_fma_f32 v[148:149], v[146:147], v[122:123], v[248:249]
	v_mul_f32_e32 v146, v151, v151
	v_mul_f32_e32 v147, v153, v153
	v_fmac_f32_e32 v146, v150, v150
	v_fmac_f32_e32 v147, v152, v152
	v_add_f32_e32 v146, v146, v147
	v_mul_f32_e32 v147, v149, v149
	v_fmac_f32_e32 v147, v148, v148
	v_add_f32_e32 v146, v146, v147
	v_mul_f32_e32 v147, v247, v247
	v_fmac_f32_e32 v147, v246, v246
	v_add_f32_e32 v245, v147, v146
	v_cvt_pk_f16_f32 v146, v150, v151
	v_cvt_f32_f16_sdwa v151, v2 dst_sel:DWORD dst_unused:UNUSED_PAD src0_sel:WORD_1
	v_cvt_f32_f16_e32 v150, v2
	v_cvt_f32_f16_sdwa v249, v3 dst_sel:DWORD dst_unused:UNUSED_PAD src0_sel:WORD_1
	v_cvt_f32_f16_e32 v248, v3
	v_cvt_pk_f16_f32 v147, v152, v153
	v_cvt_f32_f16_sdwa v153, v4 dst_sel:DWORD dst_unused:UNUSED_PAD src0_sel:WORD_1
	v_cvt_f32_f16_e32 v152, v4
	v_cvt_f32_f16_sdwa v251, v5 dst_sel:DWORD dst_unused:UNUSED_PAD src0_sel:WORD_1
	v_cvt_f32_f16_e32 v250, v5
	v_pk_fma_f32 v[144:145], v[144:145], v[120:121], v[248:249]
	v_pk_fma_f32 v[142:143], v[142:143], v[118:119], v[150:151]
	v_pk_fma_f32 v[152:153], v[138:139], v[110:111], v[152:153]
	v_mul_f32_e32 v138, v143, v143
	v_mul_f32_e32 v139, v145, v145
	v_fmac_f32_e32 v138, v142, v142
	v_fmac_f32_e32 v139, v144, v144
	v_add_f32_e32 v138, v138, v139
	v_mul_f32_e32 v139, v153, v153
	v_pk_fma_f32 v[150:151], v[140:141], v[112:113], v[250:251]
	v_fmac_f32_e32 v139, v152, v152
	v_add_f32_e32 v138, v138, v139
	v_mul_f32_e32 v139, v151, v151
	v_fmac_f32_e32 v139, v150, v150
	v_add_f32_e32 v138, v139, v138
	v_add_f32_e32 v138, v245, v138
	ds_bpermute_b32 v139, v244, v138
	v_cvt_pk_f16_f32 v148, v148, v149
	v_cvt_pk_f16_f32 v149, v246, v247
	v_cvt_pk_f16_f32 v140, v142, v143
	v_cvt_pk_f16_f32 v141, v144, v145
	s_waitcnt lgkmcnt(0)
	v_add_f32_e32 v138, v138, v139
	ds_bpermute_b32 v139, v243, v138
	v_cvt_pk_f16_f32 v142, v152, v153
	v_cvt_pk_f16_f32 v143, v150, v151
	global_store_dwordx4 v[212:213], v[146:149], off
	global_store_dwordx4 v[212:213], v[140:143], off offset:256
	s_and_saveexec_b64 s[46:47], s[38:39]
	s_cbranch_execz .LBB0_797
	v_lshl_add_u64 v[140:141], v[210:211], 2, s[86:87]
	s_waitcnt lgkmcnt(0)
	v_add_f32_e32 v138, v138, v139
	global_atomic_add_f32 v[140:141], v138, off
.LBB0_797:
	s_or_b64 exec, exec, s[46:47]
	v_or_b32_e32 v146, 16, v214
	v_ashrrev_i32_e32 v147, 31, v146
	s_waitcnt lgkmcnt(0)
	v_lshlrev_b64 v[138:139], 11, v[146:147]
	v_lshl_add_u64 v[138:139], s[60:61], 0, v[138:139]
	v_lshl_add_u64 v[148:149], v[222:223], 1, v[138:139]
	global_load_dwordx4 v[142:145], v[148:149], off
	global_load_dwordx4 v[138:141], v[148:149], off offset:256
	s_waitcnt vmcnt(10)
	v_cvt_f32_f16_sdwa v151, v182 dst_sel:DWORD dst_unused:UNUSED_PAD src0_sel:WORD_1
	v_cvt_f32_f16_e32 v150, v182
	v_cvt_f32_f16_sdwa v211, v183 dst_sel:DWORD dst_unused:UNUSED_PAD src0_sel:WORD_1
	v_cvt_f32_f16_e32 v210, v183
	v_cvt_f32_f16_sdwa v153, v184 dst_sel:DWORD dst_unused:UNUSED_PAD src0_sel:WORD_1
	v_cvt_f32_f16_sdwa v183, v185 dst_sel:DWORD dst_unused:UNUSED_PAD src0_sel:WORD_1
	v_cvt_f32_f16_e32 v182, v185
	v_cvt_f32_f16_e32 v152, v184
	v_pk_fma_f32 v[136:137], v[136:137], v[128:129], v[210:211]
	v_pk_fma_f32 v[134:135], v[134:135], v[126:127], v[150:151]
	v_pk_fma_f32 v[150:151], v[132:133], v[124:125], v[182:183]
	v_pk_fma_f32 v[132:133], v[130:131], v[122:123], v[152:153]
	v_mul_f32_e32 v130, v135, v135
	v_mul_f32_e32 v131, v137, v137
	v_fmac_f32_e32 v130, v134, v134
	v_fmac_f32_e32 v131, v136, v136
	v_add_f32_e32 v130, v130, v131
	v_mul_f32_e32 v131, v133, v133
	v_fmac_f32_e32 v131, v132, v132
	v_add_f32_e32 v130, v131, v130
	v_mul_f32_e32 v131, v151, v151
	v_fmac_f32_e32 v131, v150, v150
	v_add_f32_e32 v182, v131, v130
	v_cvt_pk_f16_f32 v130, v134, v135
	v_cvt_f32_f16_sdwa v135, v178 dst_sel:DWORD dst_unused:UNUSED_PAD src0_sel:WORD_1
	v_cvt_f32_f16_e32 v134, v178
	v_cvt_f32_f16_sdwa v153, v179 dst_sel:DWORD dst_unused:UNUSED_PAD src0_sel:WORD_1
	v_cvt_f32_f16_e32 v152, v179
	v_cvt_pk_f16_f32 v131, v136, v137
	v_cvt_f32_f16_sdwa v137, v180 dst_sel:DWORD dst_unused:UNUSED_PAD src0_sel:WORD_1
	v_cvt_f32_f16_e32 v136, v180
	v_cvt_f32_f16_sdwa v179, v181 dst_sel:DWORD dst_unused:UNUSED_PAD src0_sel:WORD_1
	v_cvt_f32_f16_e32 v178, v181
	v_pk_fma_f32 v[116:117], v[116:117], v[120:121], v[152:153]
	v_pk_fma_f32 v[114:115], v[114:115], v[118:119], v[134:135]
	v_pk_fma_f32 v[134:135], v[106:107], v[110:111], v[136:137]
	v_mul_f32_e32 v106, v115, v115
	v_mul_f32_e32 v107, v117, v117
	v_fmac_f32_e32 v106, v114, v114
	v_fmac_f32_e32 v107, v116, v116
	v_add_f32_e32 v106, v106, v107
	v_mul_f32_e32 v107, v135, v135
	v_pk_fma_f32 v[108:109], v[108:109], v[112:113], v[178:179]
	v_fmac_f32_e32 v107, v134, v134
	v_add_f32_e32 v106, v107, v106
	v_mul_f32_e32 v107, v109, v109
	v_fmac_f32_e32 v107, v108, v108
	v_add_f32_e32 v106, v107, v106
	v_add_f32_e32 v106, v182, v106
	ds_bpermute_b32 v107, v244, v106
	v_cvt_pk_f16_f32 v132, v132, v133
	v_cvt_pk_f16_f32 v133, v150, v151
	v_cvt_pk_f16_f32 v114, v114, v115
	v_cvt_pk_f16_f32 v115, v116, v117
	s_waitcnt lgkmcnt(0)
	v_add_f32_e32 v106, v106, v107
	ds_bpermute_b32 v107, v243, v106
	v_cvt_pk_f16_f32 v116, v134, v135
	v_cvt_pk_f16_f32 v117, v108, v109
	global_store_dwordx4 v[230:231], v[130:133], off
	global_store_dwordx4 v[230:231], v[114:117], off offset:256
	s_and_saveexec_b64 s[46:47], s[38:39]
	s_cbranch_execz .LBB0_799
	v_lshl_add_u64 v[108:109], v[228:229], 2, s[86:87]
	s_waitcnt lgkmcnt(0)
	v_add_f32_e32 v106, v106, v107
	global_atomic_add_f32 v[108:109], v106, off
.LBB0_799:
	s_or_b64 exec, exec, s[46:47]
	v_or_b32_e32 v130, 32, v214
	v_ashrrev_i32_e32 v131, 31, v130
	s_waitcnt lgkmcnt(0)
	v_lshlrev_b64 v[106:107], 11, v[130:131]
	v_lshl_add_u64 v[106:107], s[60:61], 0, v[106:107]
	v_lshl_add_u64 v[132:133], v[222:223], 1, v[106:107]
	global_load_dwordx4 v[114:117], v[132:133], off
	global_load_dwordx4 v[106:109], v[132:133], off offset:256
	s_waitcnt vmcnt(12)
	v_cvt_f32_f16_sdwa v135, v174 dst_sel:DWORD dst_unused:UNUSED_PAD src0_sel:WORD_1
	v_cvt_f32_f16_e32 v134, v174
	v_cvt_f32_f16_sdwa v151, v175 dst_sel:DWORD dst_unused:UNUSED_PAD src0_sel:WORD_1
	v_cvt_f32_f16_e32 v150, v175
	v_cvt_f32_f16_sdwa v137, v176 dst_sel:DWORD dst_unused:UNUSED_PAD src0_sel:WORD_1
	v_cvt_f32_f16_sdwa v153, v177 dst_sel:DWORD dst_unused:UNUSED_PAD src0_sel:WORD_1
	v_cvt_f32_f16_e32 v152, v177
	v_cvt_f32_f16_e32 v136, v176
	v_pk_fma_f32 v[104:105], v[104:105], v[128:129], v[150:151]
	v_pk_fma_f32 v[102:103], v[102:103], v[126:127], v[134:135]
	v_pk_fma_f32 v[134:135], v[100:101], v[124:125], v[152:153]
	v_pk_fma_f32 v[100:101], v[98:99], v[122:123], v[136:137]
	v_mul_f32_e32 v98, v103, v103
	v_mul_f32_e32 v99, v105, v105
	v_fmac_f32_e32 v98, v102, v102
	v_fmac_f32_e32 v99, v104, v104
	v_add_f32_e32 v98, v98, v99
	v_mul_f32_e32 v99, v101, v101
	v_fmac_f32_e32 v99, v100, v100
	v_add_f32_e32 v98, v99, v98
	v_mul_f32_e32 v99, v135, v135
	v_fmac_f32_e32 v99, v134, v134
	v_add_f32_e32 v152, v99, v98
	v_cvt_pk_f16_f32 v98, v102, v103
	v_cvt_f32_f16_sdwa v103, v170 dst_sel:DWORD dst_unused:UNUSED_PAD src0_sel:WORD_1
	v_cvt_f32_f16_e32 v102, v170
	v_cvt_f32_f16_sdwa v137, v171 dst_sel:DWORD dst_unused:UNUSED_PAD src0_sel:WORD_1
	v_cvt_f32_f16_e32 v136, v171
	v_cvt_pk_f16_f32 v99, v104, v105
	v_cvt_f32_f16_sdwa v105, v172 dst_sel:DWORD dst_unused:UNUSED_PAD src0_sel:WORD_1
	v_cvt_f32_f16_e32 v104, v172
	v_cvt_f32_f16_sdwa v151, v173 dst_sel:DWORD dst_unused:UNUSED_PAD src0_sel:WORD_1
	v_cvt_f32_f16_e32 v150, v173
	v_pk_fma_f32 v[96:97], v[96:97], v[120:121], v[136:137]
	v_pk_fma_f32 v[94:95], v[94:95], v[118:119], v[102:103]
	v_pk_fma_f32 v[104:105], v[90:91], v[110:111], v[104:105]
	v_mul_f32_e32 v90, v95, v95
	v_mul_f32_e32 v91, v97, v97
	v_fmac_f32_e32 v90, v94, v94
	v_fmac_f32_e32 v91, v96, v96
	v_add_f32_e32 v90, v90, v91
	v_mul_f32_e32 v91, v105, v105
	v_pk_fma_f32 v[102:103], v[92:93], v[112:113], v[150:151]
	v_fmac_f32_e32 v91, v104, v104
	v_add_f32_e32 v90, v91, v90
	v_mul_f32_e32 v91, v103, v103
	v_fmac_f32_e32 v91, v102, v102
	v_add_f32_e32 v90, v91, v90
	v_add_f32_e32 v90, v152, v90
	ds_bpermute_b32 v91, v244, v90
	v_cvt_pk_f16_f32 v100, v100, v101
	v_cvt_pk_f16_f32 v101, v134, v135
	v_cvt_pk_f16_f32 v92, v94, v95
	v_cvt_pk_f16_f32 v93, v96, v97
	s_waitcnt lgkmcnt(0)
	v_add_f32_e32 v90, v90, v91
	ds_bpermute_b32 v91, v243, v90
	v_cvt_pk_f16_f32 v94, v104, v105
	v_cvt_pk_f16_f32 v95, v102, v103
	global_store_dwordx4 v[226:227], v[98:101], off
	global_store_dwordx4 v[226:227], v[92:95], off offset:256
	s_and_saveexec_b64 s[46:47], s[38:39]
	s_cbranch_execz .LBB0_801
	v_lshl_add_u64 v[92:93], v[224:225], 2, s[86:87]
	s_waitcnt lgkmcnt(0)
	v_add_f32_e32 v90, v90, v91
	global_atomic_add_f32 v[92:93], v90, off
.LBB0_801:
	s_or_b64 exec, exec, s[46:47]
	v_or_b32_e32 v98, 48, v214
	v_ashrrev_i32_e32 v99, 31, v98
	s_waitcnt lgkmcnt(0)
	v_lshlrev_b64 v[90:91], 11, v[98:99]
	v_lshl_add_u64 v[90:91], s[60:61], 0, v[90:91]
	v_lshl_add_u64 v[100:101], v[222:223], 1, v[90:91]
	global_load_dwordx4 v[94:97], v[100:101], off
	global_load_dwordx4 v[90:93], v[100:101], off offset:256
	s_waitcnt vmcnt(14)
	v_cvt_f32_f16_sdwa v103, v166 dst_sel:DWORD dst_unused:UNUSED_PAD src0_sel:WORD_1
	v_cvt_f32_f16_e32 v102, v166
	v_cvt_f32_f16_sdwa v135, v167 dst_sel:DWORD dst_unused:UNUSED_PAD src0_sel:WORD_1
	v_cvt_f32_f16_e32 v134, v167
	v_cvt_f32_f16_sdwa v105, v168 dst_sel:DWORD dst_unused:UNUSED_PAD src0_sel:WORD_1
	v_cvt_f32_f16_sdwa v137, v169 dst_sel:DWORD dst_unused:UNUSED_PAD src0_sel:WORD_1
	v_cvt_f32_f16_e32 v136, v169
	v_cvt_f32_f16_e32 v104, v168
	v_pk_fma_f32 v[88:89], v[88:89], v[128:129], v[134:135]
	v_pk_fma_f32 v[86:87], v[86:87], v[126:127], v[102:103]
	v_pk_fma_f32 v[102:103], v[84:85], v[124:125], v[136:137]
	v_pk_fma_f32 v[84:85], v[82:83], v[122:123], v[104:105]
	v_mul_f32_e32 v82, v87, v87
	v_mul_f32_e32 v83, v89, v89
	v_fmac_f32_e32 v82, v86, v86
	v_fmac_f32_e32 v83, v88, v88
	v_add_f32_e32 v82, v82, v83
	v_mul_f32_e32 v83, v85, v85
	v_fmac_f32_e32 v83, v84, v84
	v_add_f32_e32 v82, v83, v82
	v_mul_f32_e32 v83, v103, v103
	v_fmac_f32_e32 v83, v102, v102
	v_add_f32_e32 v136, v83, v82
	v_cvt_pk_f16_f32 v82, v86, v87
	v_cvt_f32_f16_sdwa v87, v162 dst_sel:DWORD dst_unused:UNUSED_PAD src0_sel:WORD_1
	v_cvt_f32_f16_e32 v86, v162
	v_cvt_f32_f16_sdwa v105, v163 dst_sel:DWORD dst_unused:UNUSED_PAD src0_sel:WORD_1
	v_cvt_f32_f16_e32 v104, v163
	v_cvt_pk_f16_f32 v83, v88, v89
	v_cvt_f32_f16_sdwa v89, v164 dst_sel:DWORD dst_unused:UNUSED_PAD src0_sel:WORD_1
	v_cvt_f32_f16_e32 v88, v164
	v_cvt_f32_f16_sdwa v135, v165 dst_sel:DWORD dst_unused:UNUSED_PAD src0_sel:WORD_1
	v_cvt_f32_f16_e32 v134, v165
	v_pk_fma_f32 v[80:81], v[80:81], v[120:121], v[104:105]
	v_pk_fma_f32 v[78:79], v[78:79], v[118:119], v[86:87]
	v_pk_fma_f32 v[88:89], v[74:75], v[110:111], v[88:89]
	v_mul_f32_e32 v74, v79, v79
	v_mul_f32_e32 v75, v81, v81
	v_fmac_f32_e32 v74, v78, v78
	v_fmac_f32_e32 v75, v80, v80
	v_add_f32_e32 v74, v74, v75
	v_mul_f32_e32 v75, v89, v89
	v_pk_fma_f32 v[86:87], v[76:77], v[112:113], v[134:135]
	v_fmac_f32_e32 v75, v88, v88
	v_add_f32_e32 v74, v75, v74
	v_mul_f32_e32 v75, v87, v87
	v_fmac_f32_e32 v75, v86, v86
	v_add_f32_e32 v74, v75, v74
	v_add_f32_e32 v74, v136, v74
	ds_bpermute_b32 v75, v244, v74
	v_cvt_pk_f16_f32 v84, v84, v85
	v_cvt_pk_f16_f32 v85, v102, v103
	v_cvt_pk_f16_f32 v76, v78, v79
	v_cvt_pk_f16_f32 v77, v80, v81
	s_waitcnt lgkmcnt(0)
	v_add_f32_e32 v74, v74, v75
	ds_bpermute_b32 v75, v243, v74
	v_cvt_pk_f16_f32 v78, v88, v89
	v_cvt_pk_f16_f32 v79, v86, v87
	global_store_dwordx4 v[220:221], v[82:85], off
	global_store_dwordx4 v[220:221], v[76:79], off offset:256
	s_and_saveexec_b64 s[46:47], s[38:39]
	s_cbranch_execz .LBB0_803
	v_lshl_add_u64 v[76:77], v[218:219], 2, s[86:87]
	s_waitcnt lgkmcnt(0)
	v_add_f32_e32 v74, v74, v75
	global_atomic_add_f32 v[76:77], v74, off
.LBB0_803:
	s_or_b64 exec, exec, s[46:47]
	s_waitcnt lgkmcnt(0)
	s_waitcnt vmcnt(14)
	v_cvt_f32_f16_sdwa v75, v158 dst_sel:DWORD dst_unused:UNUSED_PAD src0_sel:WORD_1
	v_cvt_f32_f16_e32 v74, v158
	v_cvt_f32_f16_sdwa v79, v159 dst_sel:DWORD dst_unused:UNUSED_PAD src0_sel:WORD_1
	v_cvt_f32_f16_e32 v78, v159
	v_cvt_f32_f16_sdwa v77, v160 dst_sel:DWORD dst_unused:UNUSED_PAD src0_sel:WORD_1
	v_cvt_f32_f16_sdwa v81, v161 dst_sel:DWORD dst_unused:UNUSED_PAD src0_sel:WORD_1
	v_cvt_f32_f16_e32 v80, v161
	v_cvt_f32_f16_e32 v76, v160
	v_pk_fma_f32 v[72:73], v[72:73], v[128:129], v[78:79]
	v_pk_fma_f32 v[70:71], v[70:71], v[126:127], v[74:75]
	v_pk_fma_f32 v[74:75], v[68:69], v[124:125], v[80:81]
	v_pk_fma_f32 v[68:69], v[66:67], v[122:123], v[76:77]
	v_mul_f32_e32 v66, v71, v71
	v_mul_f32_e32 v67, v73, v73
	v_fmac_f32_e32 v66, v70, v70
	v_fmac_f32_e32 v67, v72, v72
	v_add_f32_e32 v66, v66, v67
	v_mul_f32_e32 v67, v69, v69
	v_fmac_f32_e32 v67, v68, v68
	v_add_f32_e32 v66, v67, v66
	v_mul_f32_e32 v67, v75, v75
	v_fmac_f32_e32 v67, v74, v74
	v_add_f32_e32 v80, v67, v66
	v_cvt_pk_f16_f32 v66, v70, v71
	v_cvt_f32_f16_sdwa v71, v154 dst_sel:DWORD dst_unused:UNUSED_PAD src0_sel:WORD_1
	v_cvt_f32_f16_e32 v70, v154
	v_cvt_f32_f16_sdwa v77, v155 dst_sel:DWORD dst_unused:UNUSED_PAD src0_sel:WORD_1
	v_cvt_f32_f16_e32 v76, v155
	v_cvt_pk_f16_f32 v67, v72, v73
	v_cvt_f32_f16_sdwa v73, v156 dst_sel:DWORD dst_unused:UNUSED_PAD src0_sel:WORD_1
	v_cvt_f32_f16_e32 v72, v156
	v_cvt_f32_f16_sdwa v79, v157 dst_sel:DWORD dst_unused:UNUSED_PAD src0_sel:WORD_1
	v_cvt_f32_f16_e32 v78, v157
	v_pk_fma_f32 v[64:65], v[64:65], v[120:121], v[76:77]
	v_pk_fma_f32 v[62:63], v[62:63], v[118:119], v[70:71]
	v_pk_fma_f32 v[72:73], v[58:59], v[110:111], v[72:73]
	v_mul_f32_e32 v58, v63, v63
	v_mul_f32_e32 v59, v65, v65
	v_fmac_f32_e32 v58, v62, v62
	v_fmac_f32_e32 v59, v64, v64
	v_add_f32_e32 v58, v58, v59
	v_mul_f32_e32 v59, v73, v73
	v_pk_fma_f32 v[70:71], v[60:61], v[112:113], v[78:79]
	v_fmac_f32_e32 v59, v72, v72
	v_add_f32_e32 v58, v59, v58
	v_mul_f32_e32 v59, v71, v71
	v_fmac_f32_e32 v59, v70, v70
	v_add_f32_e32 v58, v59, v58
	v_add_f32_e32 v58, v80, v58
	ds_bpermute_b32 v59, v244, v58
	v_cvt_pk_f16_f32 v68, v68, v69
	v_cvt_pk_f16_f32 v69, v74, v75
	v_cvt_pk_f16_f32 v60, v62, v63
	v_cvt_pk_f16_f32 v61, v64, v65
	s_waitcnt lgkmcnt(0)
	v_add_f32_e32 v58, v58, v59
	ds_bpermute_b32 v59, v243, v58
	v_cvt_pk_f16_f32 v62, v72, v73
	v_cvt_pk_f16_f32 v63, v70, v71
	global_store_dwordx4 v[216:217], v[66:69], off
	global_store_dwordx4 v[216:217], v[60:63], off offset:256
	s_and_saveexec_b64 s[46:47], s[38:39]
	s_cbranch_execz .LBB0_805
	v_lshl_add_u64 v[60:61], v[214:215], 2, s[86:87]
	s_waitcnt lgkmcnt(0)
	v_add_f32_e32 v58, v58, v59
	global_atomic_add_f32 v[60:61], v58, off
